# v102 plus P7 block selection: per-lane top-3 of 32 packed keys by one max/med3 insertion pass (3 ops per key) instead of three max + knock-out passes
# speedup vs baseline: 1.0026x; 1.0026x over previous
.LBB0_860:
	s_nop 10
	v_ashrrev_i32_e32 v83, 31, v2
	v_or_b32_e32 v83, 0x80000000, v83
	v_bitop3_b32 v2, v83, s57, v2 bitop3:0x48
	v_ashrrev_i32_e32 v83, 31, v3
	v_ashrrev_i32_e32 v85, 31, v18
	v_or_b32_e32 v83, 0x80000000, v83
	v_or_b32_e32 v85, 0x80000000, v85
	v_bitop3_b32 v3, v83, s57, v3 bitop3:0x48
	v_ashrrev_i32_e32 v83, 31, v4
	v_bitop3_b32 v18, v85, s57, v18 bitop3:0x48
	v_ashrrev_i32_e32 v85, 31, v19
	v_or_b32_e32 v83, 0x80000000, v83
	v_or_b32_e32 v85, 0x80000000, v85
	v_bitop3_b32 v4, v83, s57, v4 bitop3:0x48
	v_ashrrev_i32_e32 v83, 31, v5
	s_sub_i32 s18, s59, 32
	v_bitop3_b32 v18, v18, 63, v92 bitop3:0x36
	v_cmp_gt_u32_e32 vcc, s59, v92
	v_bitop3_b32 v19, v85, s57, v19 bitop3:0x48
	v_ashrrev_i32_e32 v85, 31, v20
	v_or_b32_e32 v83, 0x80000000, v83
	v_cndmask_b32_e32 v18, 0, v18, vcc
	v_bitop3_b32 v2, v2, 31, v92 bitop3:0x36
	v_cmp_gt_i32_e32 vcc, s18, v92
	v_or_b32_e32 v85, 0x80000000, v85
	v_bitop3_b32 v5, v83, s57, v5 bitop3:0x48
	v_ashrrev_i32_e32 v83, 31, v6
	v_cndmask_b32_e32 v2, 0, v2, vcc
	v_bitop3_b32 v19, v19, 62, v92 bitop3:0x36
	v_cmp_gt_u32_e32 vcc, s59, v106
	v_bitop3_b32 v20, v85, s57, v20 bitop3:0x48
	v_ashrrev_i32_e32 v85, 31, v21
	v_or_b32_e32 v83, 0x80000000, v83
	v_cndmask_b32_e32 v19, 0, v19, vcc
	v_bitop3_b32 v3, v3, 30, v92 bitop3:0x36
	v_cmp_gt_i32_e32 vcc, s18, v106
	v_or_b32_e32 v85, 0x80000000, v85
	v_bitop3_b32 v6, v83, s57, v6 bitop3:0x48
	v_ashrrev_i32_e32 v83, 31, v7
	v_cndmask_b32_e32 v3, 0, v3, vcc
	v_bitop3_b32 v20, v20, 61, v92 bitop3:0x36
	v_cmp_gt_u32_e32 vcc, s59, v95
	v_bitop3_b32 v21, v85, s57, v21 bitop3:0x48
	v_ashrrev_i32_e32 v85, 31, v22
	v_or_b32_e32 v83, 0x80000000, v83
	v_cndmask_b32_e32 v20, 0, v20, vcc
	v_bitop3_b32 v4, v4, 29, v92 bitop3:0x36
	v_cmp_gt_i32_e32 vcc, s18, v95
	v_or_b32_e32 v85, 0x80000000, v85
	v_bitop3_b32 v7, v83, s57, v7 bitop3:0x48
	v_ashrrev_i32_e32 v83, 31, v8
	v_cndmask_b32_e32 v4, 0, v4, vcc
	v_bitop3_b32 v21, v21, 60, v92 bitop3:0x36
	v_cmp_gt_u32_e32 vcc, s59, v107
	v_bitop3_b32 v22, v85, s57, v22 bitop3:0x48
	v_ashrrev_i32_e32 v85, 31, v23
	v_or_b32_e32 v83, 0x80000000, v83
	v_cndmask_b32_e32 v21, 0, v21, vcc
	v_bitop3_b32 v5, v5, 28, v92 bitop3:0x36
	v_cmp_gt_i32_e32 vcc, s18, v107
	v_sub_u32_e32 v22, v22, v92
	v_or_b32_e32 v85, 0x80000000, v85
	v_bitop3_b32 v8, v83, s57, v8 bitop3:0x48
	v_ashrrev_i32_e32 v83, 31, v9
	v_cndmask_b32_e32 v5, 0, v5, vcc
	v_add_u32_e32 v22, 55, v22
	v_cmp_gt_u32_e32 vcc, s59, v96
	v_sub_u32_e32 v6, v6, v92
	v_bitop3_b32 v23, v85, s57, v23 bitop3:0x48
	v_ashrrev_i32_e32 v85, 31, v24
	v_or_b32_e32 v83, 0x80000000, v83
	v_cndmask_b32_e32 v22, 0, v22, vcc
	v_add_u32_e32 v6, 23, v6
	v_cmp_gt_i32_e32 vcc, s18, v96
	v_sub_u32_e32 v23, v23, v92
	v_or_b32_e32 v85, 0x80000000, v85
	v_bitop3_b32 v9, v83, s57, v9 bitop3:0x48
	v_ashrrev_i32_e32 v83, 31, v10
	v_cndmask_b32_e32 v6, 0, v6, vcc
	v_add_u32_e32 v23, 54, v23
	v_cmp_gt_u32_e32 vcc, s59, v108
	v_sub_u32_e32 v7, v7, v92
	v_bitop3_b32 v24, v85, s57, v24 bitop3:0x48
	v_ashrrev_i32_e32 v85, 31, v25
	v_or_b32_e32 v83, 0x80000000, v83
	v_cndmask_b32_e32 v23, 0, v23, vcc
	v_add_u32_e32 v7, 22, v7
	v_cmp_gt_i32_e32 vcc, s18, v108
	v_sub_u32_e32 v24, v24, v92
	v_or_b32_e32 v85, 0x80000000, v85
	v_bitop3_b32 v10, v83, s57, v10 bitop3:0x48
	v_ashrrev_i32_e32 v83, 31, v11
	v_cndmask_b32_e32 v7, 0, v7, vcc
	v_add_u32_e32 v24, 53, v24
	v_cmp_gt_u32_e32 vcc, s59, v97
	v_sub_u32_e32 v8, v8, v92
	v_bitop3_b32 v25, v85, s57, v25 bitop3:0x48
	v_ashrrev_i32_e32 v85, 31, v26
	v_or_b32_e32 v83, 0x80000000, v83
	v_cndmask_b32_e32 v24, 0, v24, vcc
	v_add_u32_e32 v8, 21, v8
	v_cmp_gt_i32_e32 vcc, s18, v97
	v_sub_u32_e32 v25, v25, v92
	v_or_b32_e32 v85, 0x80000000, v85
	v_bitop3_b32 v11, v83, s57, v11 bitop3:0x48
	v_ashrrev_i32_e32 v83, 31, v12
	v_cndmask_b32_e32 v8, 0, v8, vcc
	v_add_u32_e32 v25, 52, v25
	v_cmp_gt_u32_e32 vcc, s59, v109
	v_sub_u32_e32 v9, v9, v92
	v_bitop3_b32 v26, v85, s57, v26 bitop3:0x48
	v_ashrrev_i32_e32 v85, 31, v27
	v_or_b32_e32 v83, 0x80000000, v83
	v_cndmask_b32_e32 v25, 0, v25, vcc
	v_add_u32_e32 v9, 20, v9
	v_cmp_gt_i32_e32 vcc, s18, v109
	v_sub_u32_e32 v26, v26, v92
	v_or_b32_e32 v85, 0x80000000, v85
	v_bitop3_b32 v12, v83, s57, v12 bitop3:0x48
	v_ashrrev_i32_e32 v83, 31, v13
	v_cndmask_b32_e32 v9, 0, v9, vcc
	v_add_u32_e32 v26, 47, v26
	v_cmp_gt_u32_e32 vcc, s59, v98
	v_bitop3_b32 v27, v85, s57, v27 bitop3:0x48
	v_ashrrev_i32_e32 v85, 31, v28
	v_or_b32_e32 v83, 0x80000000, v83
	v_cndmask_b32_e32 v26, 0, v26, vcc
	v_bitop3_b32 v10, v10, 15, v92 bitop3:0x36
	v_cmp_gt_i32_e32 vcc, s18, v98
	v_sub_u32_e32 v27, v27, v92
	v_or_b32_e32 v85, 0x80000000, v85
	v_bitop3_b32 v13, v83, s57, v13 bitop3:0x48
	v_ashrrev_i32_e32 v83, 31, v14
	v_cndmask_b32_e32 v10, 0, v10, vcc
	v_add_u32_e32 v27, 46, v27
	v_cmp_gt_u32_e32 vcc, s59, v110
	v_sub_u32_e32 v11, v11, v92
	v_bitop3_b32 v28, v85, s57, v28 bitop3:0x48
	v_ashrrev_i32_e32 v85, 31, v29
	v_or_b32_e32 v83, 0x80000000, v83
	v_cndmask_b32_e32 v27, 0, v27, vcc
	v_add_u32_e32 v11, 14, v11
	v_cmp_gt_i32_e32 vcc, s18, v110
	v_sub_u32_e32 v28, v28, v92
	v_or_b32_e32 v85, 0x80000000, v85
	v_bitop3_b32 v14, v83, s57, v14 bitop3:0x48
	v_ashrrev_i32_e32 v83, 31, v15
	v_cndmask_b32_e32 v11, 0, v11, vcc
	v_add_u32_e32 v28, 45, v28
	v_cmp_gt_u32_e32 vcc, s59, v99
	v_sub_u32_e32 v12, v12, v92
	v_bitop3_b32 v29, v85, s57, v29 bitop3:0x48
	v_ashrrev_i32_e32 v85, 31, v30
	v_or_b32_e32 v83, 0x80000000, v83
	v_cndmask_b32_e32 v28, 0, v28, vcc
	v_add_u32_e32 v12, 13, v12
	v_cmp_gt_i32_e32 vcc, s18, v99
	v_sub_u32_e32 v29, v29, v92
	v_or_b32_e32 v85, 0x80000000, v85
	v_bitop3_b32 v15, v83, s57, v15 bitop3:0x48
	v_ashrrev_i32_e32 v83, 31, v16
	v_cndmask_b32_e32 v12, 0, v12, vcc
	v_add_u32_e32 v29, 44, v29
	v_cmp_gt_u32_e32 vcc, s59, v111
	v_sub_u32_e32 v13, v13, v92
	v_bitop3_b32 v30, v85, s57, v30 bitop3:0x48
	v_ashrrev_i32_e32 v85, 31, v31
	v_or_b32_e32 v83, 0x80000000, v83
	v_cndmask_b32_e32 v29, 0, v29, vcc
	v_add_u32_e32 v13, 12, v13
	v_cmp_gt_i32_e32 vcc, s18, v111
	v_sub_u32_e32 v30, v30, v92
	v_or_b32_e32 v85, 0x80000000, v85
	v_bitop3_b32 v16, v83, s57, v16 bitop3:0x48
	v_ashrrev_i32_e32 v83, 31, v17
	v_cndmask_b32_e32 v13, 0, v13, vcc
	v_add_u32_e32 v30, 39, v30
	v_cmp_gt_u32_e32 vcc, s59, v100
	v_bitop3_b32 v31, v85, s57, v31 bitop3:0x48
	v_ashrrev_i32_e32 v85, 31, v32
	v_or_b32_e32 v83, 0x80000000, v83
	v_cndmask_b32_e32 v30, 0, v30, vcc
	v_bitop3_b32 v14, v14, 7, v92 bitop3:0x36
	v_cmp_gt_i32_e32 vcc, s18, v100
	v_sub_u32_e32 v31, v31, v92
	v_or_b32_e32 v85, 0x80000000, v85
	v_bitop3_b32 v17, v83, s57, v17 bitop3:0x48
	s_nop 0
	v_cndmask_b32_e32 v14, 0, v14, vcc
	v_add_u32_e32 v31, 38, v31
	v_cmp_gt_u32_e32 vcc, s59, v112
	v_sub_u32_e32 v15, v15, v92
	v_bitop3_b32 v32, v85, s57, v32 bitop3:0x48
	v_ashrrev_i32_e32 v85, 31, v33
	s_nop 0
	v_cndmask_b32_e32 v31, 0, v31, vcc
	v_add_u32_e32 v15, 6, v15
	v_cmp_gt_i32_e32 vcc, s18, v112
	v_sub_u32_e32 v32, v32, v92
	v_or_b32_e32 v85, 0x80000000, v85
	s_nop 0
	v_cndmask_b32_e32 v15, 0, v15, vcc
	v_add_u32_e32 v32, 37, v32
	v_cmp_gt_u32_e32 vcc, s59, v101
	v_sub_u32_e32 v16, v16, v92
	v_bitop3_b32 v33, v85, s57, v33 bitop3:0x48
	s_nop 0
	v_cndmask_b32_e32 v32, 0, v32, vcc
	v_add_u32_e32 v16, 5, v16
	v_cmp_gt_i32_e32 vcc, s18, v101
	v_sub_u32_e32 v33, v33, v92
	s_nop 0
	v_cndmask_b32_e32 v16, 0, v16, vcc
	v_add_u32_e32 v33, 36, v33
	v_cmp_gt_u32_e32 vcc, s59, v113
	s_nop 0
	s_nop 0
	v_cndmask_b32_e32 v33, 0, v33, vcc
	s_nop 0
	s_nop 0
	s_nop 0
	s_nop 0
	s_nop 0
	v_sub_u32_e32 v17, v17, v92
	s_nop 0
	v_add_u32_e32 v17, 4, v17
	v_cmp_gt_i32_e32 vcc, s18, v113
	s_nop 0
	s_nop 0
	v_cndmask_b32_e32 v17, 0, v17, vcc
	s_nop 0
	s_nop 1
	v_max_u32_e32 v85, v18, v19
	v_min_u32_e32 v86, v18, v19
	v_mov_b32_e32 v127, 0
	v_med3_u32 v127, v86, v127, v20
	v_med3_u32 v86, v85, v86, v20
	v_max_u32_e32 v85, v85, v20
	v_med3_u32 v127, v86, v127, v21
	v_med3_u32 v86, v85, v86, v21
	v_max_u32_e32 v85, v85, v21
	v_med3_u32 v127, v86, v127, v22
	v_med3_u32 v86, v85, v86, v22
	v_max_u32_e32 v85, v85, v22
	v_med3_u32 v127, v86, v127, v23
	v_med3_u32 v86, v85, v86, v23
	v_max_u32_e32 v85, v85, v23
	v_med3_u32 v127, v86, v127, v24
	v_med3_u32 v86, v85, v86, v24
	v_max_u32_e32 v85, v85, v24
	v_med3_u32 v127, v86, v127, v25
	v_med3_u32 v86, v85, v86, v25
	v_max_u32_e32 v85, v85, v25
	v_med3_u32 v127, v86, v127, v26
	v_med3_u32 v86, v85, v86, v26
	v_max_u32_e32 v85, v85, v26
	v_med3_u32 v127, v86, v127, v27
	v_med3_u32 v86, v85, v86, v27
	v_max_u32_e32 v85, v85, v27
	v_med3_u32 v127, v86, v127, v28
	v_med3_u32 v86, v85, v86, v28
	v_max_u32_e32 v85, v85, v28
	v_med3_u32 v127, v86, v127, v29
	v_med3_u32 v86, v85, v86, v29
	v_max_u32_e32 v85, v85, v29
	v_med3_u32 v127, v86, v127, v30
	v_med3_u32 v86, v85, v86, v30
	v_max_u32_e32 v85, v85, v30
	v_med3_u32 v127, v86, v127, v31
	v_med3_u32 v86, v85, v86, v31
	v_max_u32_e32 v85, v85, v31
	v_med3_u32 v127, v86, v127, v32
	v_med3_u32 v86, v85, v86, v32
	v_max_u32_e32 v85, v85, v32
	v_med3_u32 v127, v86, v127, v33
	v_med3_u32 v86, v85, v86, v33
	v_max_u32_e32 v85, v85, v33
	v_med3_u32 v127, v86, v127, v2
	v_med3_u32 v86, v85, v86, v2
	v_max_u32_e32 v85, v85, v2
	v_med3_u32 v127, v86, v127, v3
	v_med3_u32 v86, v85, v86, v3
	v_max_u32_e32 v85, v85, v3
	v_med3_u32 v127, v86, v127, v4
	v_med3_u32 v86, v85, v86, v4
	v_max_u32_e32 v85, v85, v4
	v_med3_u32 v127, v86, v127, v5
	v_med3_u32 v86, v85, v86, v5
	v_max_u32_e32 v85, v85, v5
	v_med3_u32 v127, v86, v127, v6
	v_med3_u32 v86, v85, v86, v6
	v_max_u32_e32 v85, v85, v6
	v_med3_u32 v127, v86, v127, v7
	v_med3_u32 v86, v85, v86, v7
	v_max_u32_e32 v85, v85, v7
	v_med3_u32 v127, v86, v127, v8
	v_med3_u32 v86, v85, v86, v8
	v_max_u32_e32 v85, v85, v8
	v_med3_u32 v127, v86, v127, v9
	v_med3_u32 v86, v85, v86, v9
	v_max_u32_e32 v85, v85, v9
	v_med3_u32 v127, v86, v127, v10
	v_med3_u32 v86, v85, v86, v10
	v_max_u32_e32 v85, v85, v10
	v_med3_u32 v127, v86, v127, v11
	v_med3_u32 v86, v85, v86, v11
	v_max_u32_e32 v85, v85, v11
	v_med3_u32 v127, v86, v127, v12
	v_med3_u32 v86, v85, v86, v12
	v_max_u32_e32 v85, v85, v12
	v_med3_u32 v127, v86, v127, v13
	v_med3_u32 v86, v85, v86, v13
	v_max_u32_e32 v85, v85, v13
	v_med3_u32 v127, v86, v127, v14
	v_med3_u32 v86, v85, v86, v14
	v_max_u32_e32 v85, v85, v14
	v_med3_u32 v127, v86, v127, v15
	v_med3_u32 v86, v85, v86, v15
	v_max_u32_e32 v85, v85, v15
	v_med3_u32 v127, v86, v127, v16
	v_med3_u32 v86, v85, v86, v16
	v_max_u32_e32 v85, v85, v16
	v_med3_u32 v127, v86, v127, v17
	v_med3_u32 v86, v85, v86, v17
	v_max_u32_e32 v85, v85, v17
	v_mov_b32_e32 v2, v127
	v_and_b32_e32 v8, 64, v126
	v_add_u32_e32 v4, 64, v8
	v_xor_b32_e32 v3, 32, v126
	v_cmp_lt_i32_e32 vcc, v3, v4
	v_max3_u32 v6, v85, v86, v2
	s_nop 0
	v_cndmask_b32_e32 v3, v126, v3, vcc
	v_lshlrev_b32_e32 v3, 2, v3
	ds_bpermute_b32 v4, v3, v85
	ds_bpermute_b32 v5, v3, v86
	ds_bpermute_b32 v3, v3, v2
	s_waitcnt lgkmcnt(1)
	v_max3_u32 v6, v6, v4, v5
	s_waitcnt lgkmcnt(0)
	v_max_u32_e32 v7, v6, v3
	v_cmp_ne_u32_e32 vcc, v85, v7
	s_nop 1
	v_cndmask_b32_e32 v9, 0, v85, vcc
	v_cmp_ne_u32_e32 vcc, v86, v7
	s_nop 1
	v_cndmask_b32_e32 v10, 0, v86, vcc
	v_cmp_ne_u32_e32 vcc, v2, v7
	s_nop 1
	v_cndmask_b32_e32 v2, 0, v2, vcc
	v_cmp_ne_u32_e32 vcc, v4, v7
	s_nop 1
	v_cndmask_b32_e32 v4, 0, v4, vcc
	v_cmp_ne_u32_e32 vcc, v5, v7
	s_nop 1
	v_cndmask_b32_e32 v5, 0, v5, vcc
	v_cmp_lt_u32_e32 vcc, v3, v6
	v_max3_u32 v6, v9, v10, v2
	v_max3_u32 v6, v6, v4, v5
	v_cndmask_b32_e32 v3, 0, v3, vcc
	v_max_u32_e32 v11, v6, v3
	v_cmp_ne_u32_e32 vcc, v10, v11
	s_nop 1
	v_cndmask_b32_e32 v10, 0, v10, vcc
	v_max_u32_e32 v12, v9, v10
	v_cmp_eq_u32_e32 vcc, v9, v11
	s_nop 1
	v_cndmask_b32_e32 v9, v12, v10, vcc
	v_max_u32_e32 v10, v9, v2
	v_cmp_eq_u32_e32 vcc, v2, v11
	s_nop 1
	v_cndmask_b32_e32 v2, v10, v9, vcc
	v_max_u32_e32 v9, v2, v4
	v_cmp_eq_u32_e32 vcc, v4, v11
	s_nop 1
	v_cndmask_b32_e32 v2, v9, v2, vcc
	v_max_u32_e32 v4, v2, v5
	v_cmp_eq_u32_e32 vcc, v5, v11
	v_bitop3_b32 v5, v7, 63, v7 bitop3:0xc
	v_mov_b32_e32 v7, 0
	v_cndmask_b32_e32 v2, v4, v2, vcc
	v_max_u32_e32 v4, v2, v3
	v_cmp_lt_u32_e32 vcc, v3, v6
	v_bitop3_b32 v3, v11, 63, v11 bitop3:0xc
	v_mov_b32_e32 v6, 0
	v_cndmask_b32_e32 v2, v2, v4, vcc
	v_bitop3_b32 v2, v2, 63, v2 bitop3:0xc
	v_mov_b32_e32 v4, 0
	s_and_saveexec_b64 s[18:19], s[0:1]
	s_cbranch_execz .LBB0_866
	s_cmp_eq_u32 s59, 0
	s_cbranch_scc1 .LBB0_881
	v_lshl_add_u32 v4, v5, 2, 0
	ds_add_rtn_u32 v7, v4, v125 offset:32768
	v_mov_b32_e32 v4, 0
	s_cmp_lt_u32 s59, 2
	v_mov_b32_e32 v6, 0
	s_cbranch_scc1 .LBB0_864
